# band attention prompt loop: one static s_setprio 1 for waves 4-7 before the tile loop, per-segment flips around the QK MFMA chain deleted, reset at loop exit; on top of sw10
# speedup vs baseline: 1.0041x; 1.0001x over previous
; #define BISSUE(j_) do { LAS unsigned char* d_ = lds + ((j_) & (D - 1)) * STG + w * 1024; \
;         __builtin_amdgcn_global_load_lds((const unsigned*)((const char*)Kg + (size_t)(j_) * 65536 + goff), (LAS unsigned*)d_, 16, 0, 0); \
;         __builtin_amdgcn_global_load_lds((const unsigned*)((const char*)Vg + (size_t)(j_) * 65536 + goff), (LAS unsigned*)(d_ + 8192), 16, 0, 0); } while (0)
; template <int D>
; __device__ __forceinline__ void band_unit(LAS unsigned char* lds, const bf16_t* Kg, const bf16_t* Vg, const int ntile, const bf16_t* Qg, bf16_t* Og, float* ssa, const int nci, const int crel0, const LAS float* tb) {
;     const int tid = threadIdx.x, lane = tid & 63, w = __builtin_amdgcn_readfirstlane(tid >> 6), hi = lane >> 5, l31 = lane & 31;
;     constexpr int STG = 16384;
;     const int ci = w >> 1, qb = w & 1;
;     const bool wact = ci < nci;
;     const int drow = 4 * w + (lane >> 4), fdr = ((drow & 3) << 2) | ((drow >> 2) & 3);
;     const size_t goff = (size_t)drow * 2048 + (size_t)(((lane & 15) ^ fdr) << 4);
;     ...
;     bf16x8 qf[8];
;     if (wact) { const bf16_t* qp = Qg + (size_t)(64 * ci + 32 * qb + l31) * 1024 + 8 * hi;
; #pragma unroll
;         for (int i = 0; i < 8; ++i) qf[i] = *(const bf16x8*)(qp + 16 * i); }
;     else {
; #pragma unroll
;         for (int i = 0; i < 8; ++i) qf[i] = (bf16x8){0, 0, 0, 0, 0, 0, 0, 0}; }
; #pragma unroll
;     for (int j = 0; j < 4; ++j) if (j < ntile) BISSUE(j);
;     const int fl = ((l31 & 3) << 2) | ((l31 >> 2) & 3);
;     int koff[8];
; #pragma unroll
;     for (int s8 = 0; s8 < 8; ++s8) koff[s8] = 256 * l31 + (((2 * s8 + hi) ^ fl) << 4);
;     const int q4 = (lane & 15) >> 2, blk = (lane >> 4) & 1, p4 = lane & 3;
;     int voff[2][4];
; #pragma unroll
;     for (int t = 0; t < 2; ++t)
; #pragma unroll
;         for (int c = 0; c < 4; ++c) voff[t][c] = 8192 + 256 * (4 * hi + 8 * t + q4) + ((((c ^ q4) << 2) | ((2 * blk + (p4 >> 1)) ^ ((hi + 2 * t) & 3))) << 4) + 8 * (p4 & 1);
;     f32x16 o[4];
; #pragma unroll
;     for (int c = 0; c < 4; ++c)
; #pragma unroll
;         for (int r = 0; r < 16; ++r) o[c][r] = 0.f;
;     float lsum = 0.f;
;     const float cfar = tb[256];
.LBB0_592:
	s_andn2_b64 vcc, exec, s[50:51]
	s_cbranch_vccnz .LBB0_608
	s_lshl_b32 s50, s8, 1
	s_mul_i32 s8, s3, 0x420
	s_add_i32 s51, s8, 0
	s_bfe_u32 s8, s58, 0x50003
	s_lshl_b32 s68, s8, 2
	s_lshl_b32 s65, s8, 8
	s_min_u32 s8, s68, 8
	s_lshl_b32 s8, s8, 6
	s_sub_i32 s8, s65, s8
	s_add_i32 s51, s51, 0x22000
	s_lshl_b64 s[66:67], s[8:9], 11
	s_cmp_lt_u32 s68, 8
	s_cselect_b32 s8, s68, 8
	s_lshl_b32 s8, s8, 17
	s_add_u32 s8, s8, 0x80000
	v_mov_b32_e32 v2, s51
	s_add_i32 s63, s63, s15
	s_lshl_b64 s[44:45], s[44:45], 24
	ds_read_b32 v66, v2 offset:1024
	s_add_u32 s44, s44, s66
	v_add_u32_e32 v2, s64, v138
	v_mov_b32_e32 v3, v1
	s_addc_u32 s45, s45, s67
	v_lshlrev_b64 v[2:3], 11, v[2:3]
	v_lshl_add_u64 v[2:3], s[44:45], 0, v[2:3]
	v_or_b32_e32 v2, s14, v2
	v_readlane_b32 s64, v243, 39
	v_lshl_add_u64 v[2:3], v[2:3], 0, v[0:1]
	v_readlane_b32 s65, v243, 40
	v_readlane_b32 s78, v243, 53
	v_readlane_b32 s79, v243, 54
	v_mov_b32_e32 v0, 0
	v_lshl_or_b32 v67, s33, 5, v137
	s_mov_b32 s96, s86
	v_lshl_add_u64 v[120:121], s[78:79], 0, v[2:3]
	s_mov_b32 s14, 0x1c000
	s_mov_b64 s[44:45], 0
	s_mov_b32 s64, 7
	s_mov_b32 s65, 0
	v_mov_b32_e32 v2, 0
	v_mov_b32_e32 v3, v0
	v_mov_b32_e32 v4, v0
	v_mov_b32_e32 v5, v0
	v_mov_b32_e32 v6, v0
	v_mov_b32_e32 v7, v0
	v_mov_b32_e32 v8, v0
	v_mov_b32_e32 v9, v0
	v_mov_b32_e32 v10, v0
	v_mov_b32_e32 v11, v0
	v_mov_b32_e32 v12, v0
	s_waitcnt lgkmcnt(0)
	v_mov_b32_e32 v13, v0
	v_mov_b32_e32 v14, v0
	v_mov_b32_e32 v15, v0
	v_mov_b32_e32 v16, v0
	v_mov_b32_e32 v17, v0
	v_mov_b32_e32 v18, 0
	v_mov_b32_e32 v19, v0
	v_mov_b32_e32 v20, v0
	v_mov_b32_e32 v21, v0
	v_mov_b32_e32 v22, v0
	v_mov_b32_e32 v23, v0
	v_mov_b32_e32 v24, v0
	v_mov_b32_e32 v25, v0
	v_mov_b32_e32 v26, v0
	v_mov_b32_e32 v27, v0
	v_mov_b32_e32 v28, v0
	v_mov_b32_e32 v29, v0
	v_mov_b32_e32 v30, v0
	v_mov_b32_e32 v31, v0
	v_mov_b32_e32 v32, v0
	v_mov_b32_e32 v33, v0
	v_mov_b32_e32 v50, 0
	v_mov_b32_e32 v51, v0
	v_mov_b32_e32 v52, v0
	v_mov_b32_e32 v53, v0
	v_mov_b32_e32 v54, v0
	v_mov_b32_e32 v55, v0
	v_mov_b32_e32 v56, v0
	v_mov_b32_e32 v57, v0
	v_mov_b32_e32 v58, v0
	v_mov_b32_e32 v59, v0
	v_mov_b32_e32 v60, v0
	v_mov_b32_e32 v61, v0
	v_mov_b32_e32 v62, v0
	v_mov_b32_e32 v63, v0
	v_mov_b32_e32 v64, v0
	v_mov_b32_e32 v65, v0
	v_mov_b32_e32 v34, 0
	v_mov_b32_e32 v35, v0
	v_mov_b32_e32 v36, v0
	v_mov_b32_e32 v37, v0
	v_mov_b32_e32 v38, v0
	v_mov_b32_e32 v39, v0
	v_mov_b32_e32 v40, v0
	v_mov_b32_e32 v41, v0
	v_mov_b32_e32 v42, v0
	v_mov_b32_e32 v43, v0
	v_mov_b32_e32 v44, v0
	v_mov_b32_e32 v45, v0
	v_mov_b32_e32 v46, v0
	v_mov_b32_e32 v47, v0
	v_mov_b32_e32 v48, v0
	v_mov_b32_e32 v49, v0
	v_readlane_b32 s66, v243, 41
	v_readlane_b32 s67, v243, 42
	v_readlane_b32 s68, v243, 43
	v_readlane_b32 s69, v243, 44
	v_readlane_b32 s70, v243, 45
	v_readlane_b32 s71, v243, 46
	v_readlane_b32 s72, v243, 47
	v_readlane_b32 s73, v243, 48
	v_readlane_b32 s74, v243, 49
	v_readlane_b32 s75, v243, 50
	v_readlane_b32 s76, v243, 51
	v_readlane_b32 s77, v243, 52
	s_waitcnt vmcnt(0)
	s_cmp_ge_u32 s60, 4
	s_cbranch_scc0 .Lp2prio_skip
	s_setprio 1

; template <int D>
; __device__ __forceinline__ void band_unit(LAS unsigned char* lds, const bf16_t* Kg, const bf16_t* Vg, const int ntile, const bf16_t* Qg, bf16_t* Og, float* ssa, const int nci, const int crel0, const LAS float* tb) {
;     ...
;             bf16x8 kf[8];
; #pragma unroll
;             for (int s8 = 0; s8 < 8; ++s8) kf[s8] = *(const LAS bf16x8*)(st + koff[s8]);
;             asm volatile("s_waitcnt lgkmcnt(0)" : "+v"(kf[0]), "+v"(kf[1]), "+v"(kf[2]), "+v"(kf[3]), "+v"(kf[4]), "+v"(kf[5]), "+v"(kf[6]), "+v"(kf[7]) :: "memory");
;             __builtin_amdgcn_s_setprio(1);
; #pragma unroll
;             for (int s8 = 0; s8 < 8; ++s8) sc = __builtin_amdgcn_mfma_f32_32x32x16_bf16(kf[s8], qf[s8], sc, 0, 0, 0);
;             __builtin_amdgcn_s_setprio(0);
;             s16x4 va[8], vb[8];
;             { const unsigned sb = (unsigned)(size_t)st; VTR8(va, sb + voff[0][0], sb + voff[1][0], sb + voff[0][1], sb + voff[1][1]); VTR8(vb, sb + voff[0][2], sb + voff[1][2], sb + voff[0][3], sb + voff[1][3]); }
;             float pe[16];
; #pragma unroll
;             for (int r = 0; r < 16; ++r) { pe[r] = __builtin_amdgcn_exp2f(sc[r]); lsum += pe[r]; }
;             u32x4 pw0, pw1;
;             pw0.x = cvtpk(pe[0], pe[1]); pw0.y = cvtpk(pe[2], pe[3]); pw0.z = cvtpk(pe[4], pe[5]); pw0.w = cvtpk(pe[6], pe[7]);
;             pw1.x = cvtpk(pe[8], pe[9]); pw1.y = cvtpk(pe[10], pe[11]); pw1.z = cvtpk(pe[12], pe[13]); pw1.w = cvtpk(pe[14], pe[15]);
;             VTRW(8, va, pw0, pw1);
;             const bf16x8 pa0 = __builtin_bit_cast(bf16x8, pw0), pa1 = __builtin_bit_cast(bf16x8, pw1);
;             o[0] = __builtin_amdgcn_mfma_f32_32x32x16_bf16(pa0, VFR2(va[0], va[1]), o[0], 0, 0, 0); o[0] = __builtin_amdgcn_mfma_f32_32x32x16_bf16(pa1, VFR2(va[2], va[3]), o[0], 0, 0, 0);
;             o[1] = __builtin_amdgcn_mfma_f32_32x32x16_bf16(pa0, VFR2(va[4], va[5]), o[1], 0, 0, 0); o[1] = __builtin_amdgcn_mfma_f32_32x32x16_bf16(pa1, VFR2(va[6], va[7]), o[1], 0, 0, 0);
;             VTRW(0, vb, pw0, pw1);
;             o[2] = __builtin_amdgcn_mfma_f32_32x32x16_bf16(pa0, VFR2(vb[0], vb[1]), o[2], 0, 0, 0); o[2] = __builtin_amdgcn_mfma_f32_32x32x16_bf16(pa1, VFR2(vb[2], vb[3]), o[2], 0, 0, 0);
;             o[3] = __builtin_amdgcn_mfma_f32_32x32x16_bf16(pa0, VFR2(vb[4], vb[5]), o[3], 0, 0, 0); o[3] = __builtin_amdgcn_mfma_f32_32x32x16_bf16(pa1, VFR2(vb[6], vb[7]), o[3], 0, 0, 0);
.LBB0_594:
	s_mov_b32 s66, s98
	s_waitcnt lgkmcnt(0)
	s_waitcnt lgkmcnt(0)
	v_mfma_f32_32x32x16_bf16 v[68:83], v[192:195], v[84:87], v[68:83]
	v_mfma_f32_32x32x16_bf16 v[68:83], v[188:191], v[88:91], v[68:83]
	v_mfma_f32_32x32x16_bf16 v[68:83], v[184:187], v[92:95], v[68:83]
	v_mfma_f32_32x32x16_bf16 v[68:83], v[180:183], v[96:99], v[68:83]
	v_mfma_f32_32x32x16_bf16 v[68:83], v[170:173], v[100:103], v[68:83]
	v_mfma_f32_32x32x16_bf16 v[68:83], v[126:129], v[104:107], v[68:83]
	v_mfma_f32_32x32x16_bf16 v[68:83], v[122:125], v[108:111], v[68:83]
	v_mfma_f32_32x32x16_bf16 v[68:83], v[116:119], v[112:115], v[68:83]
	v_add_u32_e32 v116, s66, v152
	v_add_u32_e32 v117, s66, v156
	v_add_u32_e32 v118, s66, v153
	v_add_u32_e32 v119, s66, v157
	ds_read_b64_tr_b16 v[180:181], v116
	ds_read_b64_tr_b16 v[182:183], v117
	ds_read_b64_tr_b16 v[170:171], v116 offset:4096
	ds_read_b64_tr_b16 v[172:173], v117 offset:4096
	ds_read_b64_tr_b16 v[126:127], v118
	ds_read_b64_tr_b16 v[128:129], v119
	ds_read_b64_tr_b16 v[122:123], v118 offset:4096
	ds_read_b64_tr_b16 v[124:125], v119 offset:4096
	v_add_u32_e32 v133, s66, v154
	v_add_u32_e32 v134, s66, v158
	v_add_u32_e32 v135, s66, v155
	v_add_u32_e32 v169, s66, v159
	ds_read_b64_tr_b16 v[192:193], v133
	ds_read_b64_tr_b16 v[194:195], v134
	ds_read_b64_tr_b16 v[188:189], v133 offset:4096
	ds_read_b64_tr_b16 v[190:191], v134 offset:4096
	ds_read_b64_tr_b16 v[184:185], v135
	ds_read_b64_tr_b16 v[186:187], v169
	ds_read_b64_tr_b16 v[116:117], v135 offset:4096
	ds_read_b64_tr_b16 v[118:119], v169 offset:4096
	v_exp_f32_e32 v68, v68
	v_exp_f32_e32 v69, v69
	v_exp_f32_e32 v70, v70
	v_exp_f32_e32 v71, v71
	v_add_f32_e32 v0, v0, v68
	v_exp_f32_e32 v72, v72
	v_add_f32_e32 v0, v69, v0
	v_exp_f32_e32 v73, v73
	v_add_f32_e32 v0, v70, v0
	v_exp_f32_e32 v74, v74
	v_add_f32_e32 v0, v71, v0
	v_exp_f32_e32 v75, v75
	v_add_f32_e32 v0, v72, v0
	v_exp_f32_e32 v76, v76
	v_add_f32_e32 v0, v73, v0
	v_exp_f32_e32 v77, v77
	v_add_f32_e32 v0, v74, v0
	v_exp_f32_e32 v78, v78
	v_add_f32_e32 v0, v75, v0
	v_exp_f32_e32 v79, v79
	v_add_f32_e32 v0, v76, v0
	v_exp_f32_e32 v80, v80
	v_add_f32_e32 v0, v77, v0
	v_exp_f32_e32 v81, v81
	v_add_f32_e32 v0, v78, v0
	v_exp_f32_e32 v82, v82
	v_exp_f32_e32 v83, v83
	v_add_f32_e32 v0, v79, v0
	v_add_f32_e32 v0, v80, v0
	v_add_f32_e32 v0, v81, v0
	v_add_f32_e32 v0, v82, v0
	v_cvt_pk_bf16_f32 v68, v68, v69
	v_cvt_pk_bf16_f32 v69, v70, v71
	v_cvt_pk_bf16_f32 v70, v72, v73
	v_cvt_pk_bf16_f32 v71, v74, v75
	v_cvt_pk_bf16_f32 v72, v76, v77
	v_cvt_pk_bf16_f32 v73, v78, v79
	v_cvt_pk_bf16_f32 v74, v80, v81
	v_cvt_pk_bf16_f32 v75, v82, v83
	v_add_f32_e32 v0, v83, v0
	s_waitcnt lgkmcnt(8)
	s_nop 0
	v_mfma_f32_32x32x16_bf16 v[34:49], v[68:71], v[180:183], v[34:49]
	s_waitcnt lgkmcnt(0)
	v_mfma_f32_32x32x16_bf16 v[50:65], v[68:71], v[126:129], v[50:65]
	v_mfma_f32_32x32x16_bf16 v[18:33], v[68:71], v[192:195], v[18:33]
	v_mfma_f32_32x32x16_bf16 v[2:17], v[68:71], v[184:187], v[2:17]
	v_mfma_f32_32x32x16_bf16 v[34:49], v[72:75], v[170:173], v[34:49]
	v_mfma_f32_32x32x16_bf16 v[50:65], v[72:75], v[122:125], v[50:65]
	v_mfma_f32_32x32x16_bf16 v[18:33], v[72:75], v[188:191], v[18:33]
	v_mfma_f32_32x32x16_bf16 v[2:17], v[72:75], v[116:119], v[2:17]

; #define LAS __attribute__((address_space(3)))
; template <int D>
; __device__ __forceinline__ void band_unit(LAS unsigned char* lds, const bf16_t* Kg, const bf16_t* Vg, const int ntile, const bf16_t* Qg, bf16_t* Og, float* ssa, const int nci, const int crel0, const LAS float* tb) {
;     ...
;     asm volatile("s_waitcnt vmcnt(0) lgkmcnt(0)" ::: "memory"); __builtin_amdgcn_s_barrier(); asm volatile("" ::: "memory");
;     LAS unsigned char* stg = lds + w * 8704;
;     LAS float* lsc = (LAS float*)(lds + LSC_OFF) + w * 32;
;     if (wact) {
;         const float l = lsum + __shfl_xor(lsum, 32);
;         if (hi == 0) lsc[l31] = l;
.LBB0_609:
	s_setprio 0
	s_waitcnt vmcnt(0) lgkmcnt(0)
	s_barrier
	s_and_b64 vcc, exec, s[42:43]
	s_cbranch_vccz .LBB0_556
	ds_bpermute_b32 v66, v136, v0
	s_lshl_b32 s8, s60, 7
	s_add_i32 s14, s8, 0
	s_add_i32 s14, s14, 0x24100
	s_and_saveexec_b64 s[42:43], s[0:1]
	s_cbranch_execz .LBB0_612
	s_waitcnt lgkmcnt(0)
	v_add_f32_e32 v0, v0, v66
	v_lshl_add_u32 v66, v137, 2, s14
	ds_write_b32 v66, v0
